# baseline (speedup 1.0000x reference)
.LBB0_248:
	s_and_b32 s2, s19, 7
	v_mul_u32_u24_e32 v0, s2, v229
	s_ashr_i32 s2, s19, 3
	v_add_u32_e32 v0, s2, v0
	s_waitcnt lgkmcnt(0)
	v_sub_u32_e32 v3, 0, v0
	v_max_i32_e32 v3, v0, v3
	v_mul_hi_u32 v4, v3, v196
	v_mul_lo_u32 v5, v4, v227
	v_sub_u32_e32 v3, v3, v5
	v_add_u32_e32 v5, 1, v4
	v_cmp_ge_u32_e32 vcc, v3, v227
	v_ashrrev_i32_e32 v2, 31, v0
	s_add_i32 s19, s19, s3
	v_cndmask_b32_e32 v4, v4, v5, vcc
	v_sub_u32_e32 v5, v3, v227
	v_cndmask_b32_e32 v3, v3, v5, vcc
	v_add_u32_e32 v5, 1, v4
	v_cmp_ge_u32_e32 vcc, v3, v227
	s_and_b32 s2, s19, 7
	v_mov_b32_e32 v204, v190
	v_cndmask_b32_e32 v3, v4, v5, vcc
	v_xor_b32_e32 v3, v3, v2
	v_sub_u32_e32 v2, v3, v2
	v_mul_lo_u32 v3, v2, v227
	v_sub_u32_e32 v0, v0, v3
	v_mul_u32_u24_e32 v3, s2, v229
	s_ashr_i32 s2, s19, 3
	v_add_u32_e32 v3, s2, v3
	v_sub_u32_e32 v5, 0, v3
	v_max_i32_e32 v5, v3, v5
	v_mul_hi_u32 v6, v5, v196
	v_mul_lo_u32 v7, v6, v227
	v_sub_u32_e32 v5, v5, v7
	v_add_u32_e32 v7, 1, v6
	v_cmp_ge_u32_e32 vcc, v5, v227
	v_ashrrev_i32_e32 v4, 31, v3
	v_lshlrev_b32_e32 v2, 11, v2
	v_cndmask_b32_e32 v6, v6, v7, vcc
	v_sub_u32_e32 v7, v5, v227
	v_cndmask_b32_e32 v5, v5, v7, vcc
	v_add_u32_e32 v7, 1, v6
	v_cmp_ge_u32_e32 vcc, v5, v227
	s_movk_i32 s2, 0x700
	v_readfirstlane_b32 s30, v225
	v_cndmask_b32_e32 v5, v6, v7, vcc
	v_xor_b32_e32 v5, v5, v4
	v_sub_u32_e32 v4, v5, v4
	v_mul_lo_u32 v5, v4, v227
	v_sub_u32_e32 v3, v3, v5
	v_lshlrev_b32_e32 v5, 8, v0
	v_and_or_b32 v2, v5, s2, v2
	v_lshlrev_b32_e32 v6, 4, v204
	v_readfirstlane_b32 s60, v2
	v_bfe_i32 v2, v204, 27, 1
	v_lshrrev_b32_e32 v2, 22, v2
	v_add_u32_e32 v2, v6, v2
	v_lshlrev_b32_e32 v5, 8, v3
	v_lshlrev_b32_e32 v3, 5, v3
	v_and_b32_e32 v2, 0xfffffc00, v2
	v_lshlrev_b32_e32 v0, 5, v0
	v_and_b32_e32 v5, 0x700, v5
	v_cmp_lt_i32_e32 vcc, s19, v226
	v_and_b32_e32 v3, 0xffffff00, v3
	v_sub_u32_e32 v2, v6, v2
	v_and_b32_e32 v0, 0xffffff00, v0
	v_lshl_or_b32 v4, v4, 11, v5
	v_lshrrev_b32_e32 v9, 8, v3
	v_mov_b32_e32 v10, v9
	v_cmp_eq_u32_e64 s[8:9], 19, v9
	s_nop 1
	v_cndmask_b32_e64 v10, v10, 24, s[8:9]
	v_cmp_eq_u32_e64 s[8:9], 24, v9
	s_nop 1
	v_cndmask_b32_e64 v10, v10, 19, s[8:9]
	v_cmp_eq_u32_e64 s[8:9], 15, v9
	s_nop 1
	v_cndmask_b32_e64 v10, v10, 25, s[8:9]
	v_cmp_eq_u32_e64 s[8:9], 25, v9
	s_nop 1
	v_cndmask_b32_e64 v10, v10, 15, s[8:9]
	v_cmp_eq_u32_e64 s[8:9], 26, v9
	s_nop 1
	v_cndmask_b32_e64 v10, v10, 30, s[8:9]
	v_cmp_eq_u32_e64 s[8:9], 30, v9
	s_nop 1
	v_cndmask_b32_e64 v10, v10, 26, s[8:9]
	v_cmp_eq_u32_e64 s[8:9], 0, v9
	s_nop 1
	v_cndmask_b32_e64 v10, v10, 31, s[8:9]
	v_cmp_eq_u32_e64 s[8:9], 31, v9
	s_nop 1
	v_cndmask_b32_e64 v10, v10, 0, s[8:9]
	v_cmp_eq_u32_e64 s[8:9], 4, v9
	s_nop 1
	v_cndmask_b32_e64 v10, v10, 35, s[8:9]
	v_cmp_eq_u32_e64 s[8:9], 35, v9
	s_nop 1
	v_cndmask_b32_e64 v10, v10, 4, s[8:9]
	v_cmp_eq_u32_e64 s[8:9], 8, v9
	s_nop 1
	v_cndmask_b32_e64 v10, v10, 39, s[8:9]
	v_cmp_eq_u32_e64 s[8:9], 39, v9
	s_nop 1
	v_cndmask_b32_e64 v10, v10, 8, s[8:9]
	v_cmp_eq_u32_e64 s[8:9], 12, v9
	s_nop 1
	v_cndmask_b32_e64 v10, v10, 43, s[8:9]
	v_cmp_eq_u32_e64 s[8:9], 43, v9
	s_nop 1
	v_cndmask_b32_e64 v10, v10, 12, s[8:9]
	v_cmp_eq_u32_e64 s[8:9], 1, v9
	s_nop 1
	v_cndmask_b32_e64 v10, v10, 32, s[8:9]
	v_cmp_eq_u32_e64 s[8:9], 32, v9
	s_nop 1
	v_cndmask_b32_e64 v10, v10, 1, s[8:9]
	v_cmp_eq_u32_e64 s[8:9], 5, v9
	s_nop 1
	v_cndmask_b32_e64 v10, v10, 36, s[8:9]
	v_cmp_eq_u32_e64 s[8:9], 36, v9
	s_nop 1
	v_cndmask_b32_e64 v10, v10, 5, s[8:9]
	v_cmp_eq_u32_e64 s[8:9], 9, v9
	s_nop 1
	v_cndmask_b32_e64 v10, v10, 40, s[8:9]
	v_cmp_eq_u32_e64 s[8:9], 40, v9
	s_nop 1
	v_cndmask_b32_e64 v10, v10, 9, s[8:9]
	v_cmp_eq_u32_e64 s[8:9], 13, v9
	s_nop 1
	v_cndmask_b32_e64 v10, v10, 44, s[8:9]
	v_cmp_eq_u32_e64 s[8:9], 44, v9
	s_nop 1
	v_cndmask_b32_e64 v10, v10, 13, s[8:9]
	v_cmp_eq_u32_e64 s[8:9], 2, v9
	s_nop 1
	v_cndmask_b32_e64 v10, v10, 33, s[8:9]
	v_cmp_eq_u32_e64 s[8:9], 33, v9
	s_nop 1
	v_cndmask_b32_e64 v10, v10, 2, s[8:9]
	v_cmp_eq_u32_e64 s[8:9], 6, v9
	s_nop 1
	v_cndmask_b32_e64 v10, v10, 37, s[8:9]
	v_cmp_eq_u32_e64 s[8:9], 37, v9
	s_nop 1
	v_cndmask_b32_e64 v10, v10, 6, s[8:9]
	v_cmp_eq_u32_e64 s[8:9], 10, v9
	s_nop 1
	v_cndmask_b32_e64 v10, v10, 41, s[8:9]
	v_cmp_eq_u32_e64 s[8:9], 41, v9
	s_nop 1
	v_cndmask_b32_e64 v10, v10, 10, s[8:9]
	v_cmp_eq_u32_e64 s[8:9], 14, v9
	s_nop 1
	v_cndmask_b32_e64 v10, v10, 45, s[8:9]
	v_cmp_eq_u32_e64 s[8:9], 45, v9
	s_nop 1
	v_cndmask_b32_e64 v10, v10, 14, s[8:9]
	v_cmp_eq_u32_e64 s[8:9], 0, v224
	s_nop 1
	v_cndmask_b32_e64 v9, v9, v10, s[8:9]
	v_lshlrev_b32_e32 v3, 8, v9
	v_cndmask_b32_e32 v5, 0, v3, vcc
	v_lshrrev_b32_e32 v3, 4, v2
	v_lshrrev_b32_e32 v9, 8, v0
	v_mov_b32_e32 v10, v9
	v_cmp_eq_u32_e64 s[8:9], 19, v9
	s_nop 1
	v_cndmask_b32_e64 v10, v10, 24, s[8:9]
	v_cmp_eq_u32_e64 s[8:9], 24, v9
	s_nop 1
	v_cndmask_b32_e64 v10, v10, 19, s[8:9]
	v_cmp_eq_u32_e64 s[8:9], 15, v9
	s_nop 1
	v_cndmask_b32_e64 v10, v10, 25, s[8:9]
	v_cmp_eq_u32_e64 s[8:9], 25, v9
	s_nop 1
	v_cndmask_b32_e64 v10, v10, 15, s[8:9]
	v_cmp_eq_u32_e64 s[8:9], 26, v9
	s_nop 1
	v_cndmask_b32_e64 v10, v10, 30, s[8:9]
	v_cmp_eq_u32_e64 s[8:9], 30, v9
	s_nop 1
	v_cndmask_b32_e64 v10, v10, 26, s[8:9]
	v_cmp_eq_u32_e64 s[8:9], 0, v9
	s_nop 1
	v_cndmask_b32_e64 v10, v10, 31, s[8:9]
	v_cmp_eq_u32_e64 s[8:9], 31, v9
	s_nop 1
	v_cndmask_b32_e64 v10, v10, 0, s[8:9]
	v_cmp_eq_u32_e64 s[8:9], 4, v9
	s_nop 1
	v_cndmask_b32_e64 v10, v10, 35, s[8:9]
	v_cmp_eq_u32_e64 s[8:9], 35, v9
	s_nop 1
	v_cndmask_b32_e64 v10, v10, 4, s[8:9]
	v_cmp_eq_u32_e64 s[8:9], 8, v9
	s_nop 1
	v_cndmask_b32_e64 v10, v10, 39, s[8:9]
	v_cmp_eq_u32_e64 s[8:9], 39, v9
	s_nop 1
	v_cndmask_b32_e64 v10, v10, 8, s[8:9]
	v_cmp_eq_u32_e64 s[8:9], 12, v9
	s_nop 1
	v_cndmask_b32_e64 v10, v10, 43, s[8:9]
	v_cmp_eq_u32_e64 s[8:9], 43, v9
	s_nop 1
	v_cndmask_b32_e64 v10, v10, 12, s[8:9]
	v_cmp_eq_u32_e64 s[8:9], 1, v9
	s_nop 1
	v_cndmask_b32_e64 v10, v10, 32, s[8:9]
	v_cmp_eq_u32_e64 s[8:9], 32, v9
	s_nop 1
	v_cndmask_b32_e64 v10, v10, 1, s[8:9]
	v_cmp_eq_u32_e64 s[8:9], 5, v9
	s_nop 1
	v_cndmask_b32_e64 v10, v10, 36, s[8:9]
	v_cmp_eq_u32_e64 s[8:9], 36, v9
	s_nop 1
	v_cndmask_b32_e64 v10, v10, 5, s[8:9]
	v_cmp_eq_u32_e64 s[8:9], 9, v9
	s_nop 1
	v_cndmask_b32_e64 v10, v10, 40, s[8:9]
	v_cmp_eq_u32_e64 s[8:9], 40, v9
	s_nop 1
	v_cndmask_b32_e64 v10, v10, 9, s[8:9]
	v_cmp_eq_u32_e64 s[8:9], 13, v9
	s_nop 1
	v_cndmask_b32_e64 v10, v10, 44, s[8:9]
	v_cmp_eq_u32_e64 s[8:9], 44, v9
	s_nop 1
	v_cndmask_b32_e64 v10, v10, 13, s[8:9]
	v_cmp_eq_u32_e64 s[8:9], 2, v9
	s_nop 1
	v_cndmask_b32_e64 v10, v10, 33, s[8:9]
	v_cmp_eq_u32_e64 s[8:9], 33, v9
	s_nop 1
	v_cndmask_b32_e64 v10, v10, 2, s[8:9]
	v_cmp_eq_u32_e64 s[8:9], 6, v9
	s_nop 1
	v_cndmask_b32_e64 v10, v10, 37, s[8:9]
	v_cmp_eq_u32_e64 s[8:9], 37, v9
	s_nop 1
	v_cndmask_b32_e64 v10, v10, 6, s[8:9]
	v_cmp_eq_u32_e64 s[8:9], 10, v9
	s_nop 1
	v_cndmask_b32_e64 v10, v10, 41, s[8:9]
	v_cmp_eq_u32_e64 s[8:9], 41, v9
	s_nop 1
	v_cndmask_b32_e64 v10, v10, 10, s[8:9]
	v_cmp_eq_u32_e64 s[8:9], 14, v9
	s_nop 1
	v_cndmask_b32_e64 v10, v10, 45, s[8:9]
	v_cmp_eq_u32_e64 s[8:9], 45, v9
	s_nop 1
	v_cndmask_b32_e64 v10, v10, 14, s[8:9]
	v_cmp_eq_u32_e64 s[8:9], 0, v224
	s_nop 1
	v_cndmask_b32_e64 v9, v9, v10, s[8:9]
	v_lshlrev_b32_e32 v0, 8, v9
	s_nop 0
	v_readfirstlane_b32 s94, v0
	v_ashrrev_i32_e32 v0, 31, v204
	v_bitop3_b32 v2, v3, v2, 32 bitop3:0x6c
	v_lshrrev_b32_e32 v0, 26, v0
	v_ashrrev_i32_e32 v7, 31, v2
	v_add_u32_e32 v0, v204, v0
	v_lshrrev_b32_e32 v7, 26, v7
	v_ashrrev_i32_e32 v0, 6, v0
	v_add_u32_e32 v7, v2, v7
	v_lshlrev_b32_e32 v3, 3, v0
	v_ashrrev_i32_e32 v8, 6, v7
	v_and_b32_e32 v7, 0xc0, v7
	v_and_b32_e32 v3, 0x7ffffff0, v3
	v_lshlrev_b32_e32 v0, 5, v0
	v_sub_u32_e32 v2, v2, v7
	v_add_u32_e32 v3, v8, v3
	v_and_b32_e32 v0, 32, v0
	v_ashrrev_i16_sdwa v2, v197, sext(v2) dst_sel:DWORD dst_unused:UNUSED_PAD src0_sel:DWORD src1_sel:BYTE_0
	s_ashr_i32 s31, s30, 31
	v_bfe_i32 v7, v2, 0, 16
	v_mad_u64_u32 v[2:3], s[8:9], v3, s30, v[0:1]
	s_ashr_i32 s2, s60, 31
	s_lshl_b64 s[74:75], s[30:31], 1
	s_mul_i32 s2, s74, s2
	s_mul_hi_u32 s8, s74, s60
	s_add_i32 s2, s8, s2
	s_lshr_b64 s[8:9], s[30:31], 31
	s_mul_i32 s9, s8, s60
	v_readfirstlane_b32 s84, v194
	s_add_i32 s2, s2, s9
	s_mul_i32 s9, s74, s60
	v_readfirstlane_b32 s77, v195
	s_add_u32 s24, s84, s9
	s_addc_u32 s2, s77, s2
	s_ashr_i32 s95, s94, 31
	s_and_b32 s25, s2, 0xffff
	s_mul_i32 s2, s74, s95
	s_mul_hi_u32 s9, s74, s94
	s_add_i32 s2, s9, s2
	s_mul_i32 s8, s8, s94
	v_readfirstlane_b32 s76, v192
	s_add_i32 s2, s2, s8
	s_mul_i32 s8, s74, s94
	v_readfirstlane_b32 s83, v193
	s_add_u32 s44, s76, s8
	v_add_lshl_u32 v0, v2, v7, 1
	s_addc_u32 s2, s83, s2
	v_cndmask_b32_e64 v2, 0, 1, vcc
	s_and_b32 s45, s2, 0xffff
	v_readfirstlane_b32 s2, v2
	v_cndmask_b32_e64 v2, 0, 1, s[46:47]
	s_bitcmp1_b32 s2, 0
	v_readfirstlane_b32 s2, v2
	s_cselect_b64 s[28:29], -1, 0
	s_bitcmp1_b32 s2, 0
	v_cndmask_b32_e32 v4, 0, v4, vcc
	s_cselect_b64 s[46:47], -1, 0
	v_add_u32_e32 v232, 0, v6
	v_cmp_ge_i32_e64 s[6:7], s19, v226
	v_readfirstlane_b32 s97, v224
	v_readfirstlane_b32 s96, v228
	v_readfirstlane_b32 s13, v4
	v_readfirstlane_b32 s9, v5
	s_lshl_b32 s8, s30, 7
	s_and_b64 vcc, exec, s[46:47]
	v_add_u32_e32 v236, 0x10000, v232
	v_add_u32_e32 v235, 0x12000, v232
	v_add_u32_e32 v234, 0x2000, v232
	v_add_u32_e32 v233, 0x14000, v232
	v_add_u32_e32 v231, 0x16000, v232
	s_mul_i32 s85, s30, 0x180
	v_add_u32_e32 v230, 0x4000, v232
	v_add_u32_e32 v205, 0x6000, v232
	s_cbranch_vccnz .LBB0_250
	v_readfirstlane_b32 s2, v236
	s_mov_b32 s46, s26
	s_mov_b32 s47, s27
	s_mov_b32 m0, s2
	v_readfirstlane_b32 s2, v235
	buffer_load_dwordx4 v0, s[44:47], 0 offen lds
	s_mov_b32 m0, s2
	v_readfirstlane_b32 s2, v232
	buffer_load_dwordx4 v0, s[44:47], s8 offen lds
	s_mov_b32 m0, s2
	v_readfirstlane_b32 s2, v234
	buffer_load_dwordx4 v0, s[24:27], 0 offen lds
	s_mov_b32 m0, s2
	v_readfirstlane_b32 s33, v233
	buffer_load_dwordx4 v0, s[24:27], s8 offen lds
	s_lshl_b32 s2, s30, 8
	s_mov_b32 m0, s33
	v_readfirstlane_b32 s33, v231
	buffer_load_dwordx4 v0, s[44:47], s2 offen lds
	s_mov_b32 m0, s33
	v_readfirstlane_b32 s33, v230
	buffer_load_dwordx4 v0, s[44:47], s85 offen lds
	s_mov_b32 m0, s33
	s_nop 0
	buffer_load_dwordx4 v0, s[24:27], s2 offen lds
	v_readfirstlane_b32 s2, v205
	s_mov_b32 m0, s2
	s_nop 0
	buffer_load_dwordx4 v0, s[24:27], s85 offen lds
